# x (f32 residual base, read once) loaded non-temporal in the first down-projection epilogue
# speedup vs baseline: 1.0054x; 1.0033x over previous
;     __device__ __forceinline__ void operator()(const f32x4 (&acc)[2][2][4][2], const Unit& u, int wr, int wc, int fr, int fq) const {
;         const int row0 = u.pm * 256 + wr * 64 + fr, col0 = u.pn * 256 + wc * 32 + 8 * fq;
;         const int mb = u.pm < 64 ? (u.pm >> 4) : 4;
;         float* SSn = (float*)(ws + WS_SS) + ss_off;
;         const float* gate = (const float*)(ws + WS_MOD) + gate_off + (size_t)mb * 9216; const float* gn = (const float*)(ws + WS_NG) + gn_off; const float* scn = (const float*)(ws + WS_MOD) + scn_off + (size_t)mb * 9216;
;         f32x4 gv[2][2], bv[2][2], wv[2][2];
; #pragma unroll
;         for (int bj = 0; bj < 2; ++bj)
; #pragma unroll
;             for (int n = 0; n < 2; ++n) { const int cc = col0 + bj * 128 + 4 * n;
;                 gv[bj][n] = *(const f32x4*)(gate + cc) * gmul;
;                 bv[bj][n] = HASBIAS ? *(const f32x4*)(bias + cc) : (f32x4){0.f, 0.f, 0.f, 0.f};
;                 wv[bj][n] = FUSE ? *(const f32x4*)(gn + cc) * (*(const f32x4*)(scn + cc) + 1.0f) : (f32x4){0.f, 0.f, 0.f, 0.f}; }
;         const unsigned e0 = (unsigned)(row0 * D + col0);
;         const char* bsc = (const char*)base0; char* Hc = (char*)(ws + WS_H); char* HBc = (char*)(ws + WS_XN);
;         constexpr int RGB = 2;
; #pragma unroll
;         for (int rg = 0; rg < 8 / RGB; ++rg) {
;             u32x4 braw[INPLACE ? RGB : 1][2]; f32x4 bb[INPLACE ? 1 : RGB][2][2];
; #pragma unroll
;             for (int mm = 0; mm < RGB; ++mm) { const int q = rg * RGB + mm, ai = q >> 2, m = q & 3;
; #pragma unroll
;                 for (int bj = 0; bj < 2; ++bj) { const unsigned e = e0 + (unsigned)((ai * 128 + m * 16) * D + bj * 128);
;                     if constexpr (INPLACE) braw[mm][bj] = *(const u32x4*)(Hc + (size_t)(e * 2u));
;                     else { bb[mm][bj][0] = *(const f32x4*)(bsc + (size_t)(e * 4u)); bb[mm][bj][1] = *(const f32x4*)(bsc + (size_t)(e * 4u + 16u)); } } }
; #pragma unroll
;             for (int mm = 0; mm < RGB; ++mm) { const int q = rg * RGB + mm, ai = q >> 2, m = q & 3; float ssum = 0.f;
; #pragma unroll
;                 for (int bj = 0; bj < 2; ++bj) { const unsigned e = e0 + (unsigned)((ai * 128 + m * 16) * D + bj * 128);
;                     f32x4 r0, r1;
;                     if constexpr (INPLACE) { const u32x4 q4 = braw[mm][bj];
.LBB0_313:
	s_ashr_i32 s38, s66, 4
	v_lshl_or_b32 v20, s65, 8, v195
	s_mul_i32 s40, s38, 0x9000
	s_mul_hi_i32 s41, s38, 0x9000
	s_add_u32 s38, s57, s40
	v_ashrrev_i32_e32 v21, 31, v20
	s_addc_u32 s39, s58, s41
	v_lshlrev_b64 v[12:13], 2, v[20:21]
	v_lshl_add_u64 v[22:23], s[38:39], 0, v[12:13]
	s_waitcnt lgkmcnt(0)
	global_load_dwordx4 v[0:3], v[22:23], off offset:16
	global_load_dwordx4 v[4:7], v[22:23], off
	s_add_u32 s40, s59, s40
	s_addc_u32 s41, s60, s41
	v_lshl_add_u64 v[8:9], s[22:23], 0, v[12:13]
	v_lshl_add_u64 v[72:73], s[40:41], 0, v[12:13]
	v_lshl_add_u32 v136, s66, 8, v183
	v_lshl_add_u32 v233, v136, 10, v20
	v_lshlrev_b32_e32 v231, 2, v233
	v_add_u32_e32 v232, 0x10000, v231
	s_waitcnt vmcnt(0)
	v_pk_mul_f32 v[102:103], v[2:3], 0.5 op_sel_hi:[1,0]
	v_pk_mul_f32 v[100:101], v[6:7], 0.5 op_sel_hi:[1,0]
	v_pk_mul_f32 v[98:99], v[4:5], 0.5 op_sel_hi:[1,0]
	global_load_dwordx4 v[4:7], v[8:9], off offset:16
	s_nop 0
	global_load_dwordx4 v[8:11], v[8:9], off
	s_nop 0
	global_load_dwordx4 v[12:15], v[72:73], off offset:16
	global_load_dwordx4 v[16:19], v[72:73], off
	v_pk_mul_f32 v[96:97], v[0:1], 0.5 op_sel_hi:[1,0]
	s_waitcnt vmcnt(0)
	v_pk_add_f32 v[0:1], v[14:15], 1.0 op_sel_hi:[1,0]
	v_pk_add_f32 v[2:3], v[12:13], 1.0 op_sel_hi:[1,0]
	v_pk_mul_f32 v[78:79], v[6:7], v[0:1]
	v_pk_mul_f32 v[80:81], v[4:5], v[2:3]
	global_load_dwordx4 v[0:3], v[22:23], off offset:528
	global_load_dwordx4 v[4:7], v[22:23], off offset:512
	v_pk_add_f32 v[16:17], v[16:17], 1.0 op_sel_hi:[1,0]
	v_pk_add_f32 v[18:19], v[18:19], 1.0 op_sel_hi:[1,0]
	v_pk_mul_f32 v[76:77], v[8:9], v[16:17]
	v_or_b32_e32 v8, 0x80, v20
	v_ashrrev_i32_e32 v9, 31, v8
	v_lshl_add_u64 v[8:9], v[8:9], 2, s[22:23]
	v_pk_mul_f32 v[74:75], v[10:11], v[18:19]
	s_waitcnt vmcnt(0)
	v_pk_mul_f32 v[118:119], v[2:3], 0.5 op_sel_hi:[1,0]
	v_pk_mul_f32 v[116:117], v[6:7], 0.5 op_sel_hi:[1,0]
	v_pk_mul_f32 v[114:115], v[4:5], 0.5 op_sel_hi:[1,0]
	global_load_dwordx4 v[4:7], v[8:9], off offset:16
	s_nop 0
	global_load_dwordx4 v[8:11], v[8:9], off
	s_nop 0
	global_load_dwordx4 v[12:15], v[72:73], off offset:528
	global_load_dwordx4 v[16:19], v[72:73], off offset:512
	v_pk_mul_f32 v[112:113], v[0:1], 0.5 op_sel_hi:[1,0]
	s_waitcnt vmcnt(0)
	v_pk_add_f32 v[2:3], v[12:13], 1.0 op_sel_hi:[1,0]
	v_pk_add_f32 v[18:19], v[18:19], 1.0 op_sel_hi:[1,0]
	v_pk_add_f32 v[16:17], v[16:17], 1.0 op_sel_hi:[1,0]
	v_pk_mul_f32 v[90:91], v[10:11], v[18:19]
	v_pk_mul_f32 v[72:73], v[8:9], v[16:17]
	global_load_dwordx4 v[234:237], v231, s[16:17] offset:16 nt
	global_load_dwordx4 v[238:241], v231, s[16:17] nt
	global_load_dwordx4 v[16:19], v231, s[16:17] offset:528 nt
	global_load_dwordx4 v[20:23], v231, s[16:17] offset:512 nt
	v_pk_add_f32 v[0:1], v[14:15], 1.0 op_sel_hi:[1,0]
	v_pk_mul_f32 v[84:85], v[4:5], v[2:3]
	v_add_u32_e32 v4, 0x10200, v231
	v_pk_mul_f32 v[82:83], v[6:7], v[0:1]
	global_load_dwordx4 v[8:11], v232, s[16:17] offset:16 nt
	global_load_dwordx4 v[12:15], v232, s[16:17] nt
	global_load_dwordx4 v[0:3], v4, s[16:17] offset:16 nt
	s_nop 0
	global_load_dwordx4 v[4:7], v4, s[16:17] nt
	s_waitcnt vmcnt(0)
	v_pk_fma_f32 v[236:237], v[214:215], v[102:103], v[236:237]
	v_pk_fma_f32 v[240:241], v[210:211], v[100:101], v[240:241]
	v_pk_fma_f32 v[238:239], v[212:213], v[98:99], v[238:239]
	v_lshlrev_b32_e32 v210, 1, v233
	v_cvt_pk_bf16_f32 v212, v238, v239
	v_pk_fma_f32 v[216:217], v[216:217], v[96:97], v[234:235]
	v_cvt_pk_bf16_f32 v213, v240, v241
	v_mul_f32_e32 v211, v239, v239
	v_cvt_pk_bf16_f32 v214, v216, v217
	v_cvt_pk_bf16_f32 v215, v236, v237
	global_store_dwordx4 v210, v[212:215], s[26:27] nt
	v_fmac_f32_e32 v211, v238, v238
	v_pk_mul_f32 v[234:235], v[78:79], v[236:237]
	v_mul_f32_e32 v212, v241, v241
	v_fmac_f32_e32 v212, v240, v240
	v_add_f32_e32 v211, v211, v212
	v_mul_f32_e32 v212, v217, v217
	v_mul_f32_e32 v213, v237, v237
	v_fmac_f32_e32 v212, v216, v216
	v_fmac_f32_e32 v213, v236, v236
	v_add_f32_e32 v212, v212, v213
	v_add_f32_e32 v211, v211, v212
	v_pk_mul_f32 v[214:215], v[74:75], v[240:241]
	v_pk_mul_f32 v[212:213], v[76:77], v[238:239]
	v_pk_mul_f32 v[216:217], v[80:81], v[216:217]
	v_cvt_pk_bf16_f32 v212, v212, v213
	v_cvt_pk_bf16_f32 v213, v214, v215
	v_pk_fma_f32 v[22:23], v[208:209], v[116:117], v[22:23]
	v_cvt_pk_bf16_f32 v214, v216, v217
	v_cvt_pk_bf16_f32 v215, v234, v235
	global_store_dwordx4 v210, v[212:215], s[72:73]
	v_pk_fma_f32 v[20:21], v[206:207], v[114:115], v[20:21]
	v_pk_fma_f32 v[202:203], v[202:203], v[112:113], v[16:17]
	v_cvt_pk_bf16_f32 v16, v20, v21
	v_cvt_pk_bf16_f32 v17, v22, v23
	v_or_b32_e32 v206, 0x100, v210
	v_pk_fma_f32 v[204:205], v[204:205], v[118:119], v[18:19]
	v_cvt_pk_bf16_f32 v18, v202, v203
	s_nop 0
	v_cvt_pk_bf16_f32 v19, v204, v205
	global_store_dwordx4 v206, v[16:19], s[26:27] nt
	s_nop 1
	v_mul_f32_e32 v16, v21, v21
	v_mul_f32_e32 v17, v23, v23
	v_fmac_f32_e32 v16, v20, v20
	v_fmac_f32_e32 v17, v22, v22
	v_add_f32_e32 v16, v16, v17
	v_mul_f32_e32 v17, v203, v203
	v_mul_f32_e32 v18, v205, v205
	v_fmac_f32_e32 v17, v202, v202
	v_fmac_f32_e32 v18, v204, v204
	v_add_f32_e32 v17, v17, v18
	v_add_f32_e32 v16, v16, v17
	v_add_f32_e32 v207, v211, v16
	v_pk_mul_f32 v[16:17], v[72:73], v[20:21]
	v_pk_mul_f32 v[18:19], v[90:91], v[22:23]
	v_cvt_pk_bf16_f32 v16, v16, v17
	v_pk_mul_f32 v[20:21], v[82:83], v[204:205]
	v_cvt_pk_bf16_f32 v17, v18, v19
	v_pk_mul_f32 v[22:23], v[84:85], v[202:203]
	s_nop 0
	v_cvt_pk_bf16_f32 v18, v22, v23
	v_cvt_pk_bf16_f32 v19, v20, v21
	global_store_dwordx4 v206, v[16:19], s[72:73]
	s_nop 1
	v_and_b32_e32 v17, 64, v230
	v_xor_b32_e32 v16, 16, v230
	v_add_u32_e32 v17, 64, v17
	v_cmp_lt_i32_e32 vcc, v16, v17
	v_xor_b32_e32 v19, 32, v230
	s_nop 0
	v_cndmask_b32_e32 v16, v230, v16, vcc
	v_lshlrev_b32_e32 v16, 2, v16
	ds_bpermute_b32 v18, v16, v207
	v_cmp_lt_i32_e32 vcc, v19, v17
	s_waitcnt lgkmcnt(0)
	v_add_f32_e32 v18, v207, v18
	v_cndmask_b32_e32 v17, v230, v19, vcc
	v_lshlrev_b32_e32 v17, 2, v17
	ds_bpermute_b32 v19, v17, v18
	s_and_saveexec_b64 s[38:39], s[0:1]
	s_cbranch_execz .LBB0_315
	v_lshl_add_u64 v[20:21], v[136:137], 2, s[24:25]
	s_waitcnt lgkmcnt(0)
	v_add_f32_e32 v18, v18, v19
	global_atomic_add_f32 v[20:21], v18, off

;     __device__ __forceinline__ void operator()(const f32x4 (&acc)[2][2][4][2], const Unit& u, int wr, int wc, int fr, int fq) const {
;     ...
;         for (int rg = 0; rg < 8 / RGB; ++rg) {
;             u32x4 braw[INPLACE ? RGB : 1][2]; f32x4 bb[INPLACE ? 1 : RGB][2][2];
; #pragma unroll
;             for (int mm = 0; mm < RGB; ++mm) { const int q = rg * RGB + mm, ai = q >> 2, m = q & 3;
; #pragma unroll
;                 for (int bj = 0; bj < 2; ++bj) { const unsigned e = e0 + (unsigned)((ai * 128 + m * 16) * D + bj * 128);
;                     if constexpr (INPLACE) braw[mm][bj] = *(const u32x4*)(Hc + (size_t)(e * 2u));
;                     else { bb[mm][bj][0] = *(const f32x4*)(bsc + (size_t)(e * 4u)); bb[mm][bj][1] = *(const f32x4*)(bsc + (size_t)(e * 4u + 16u)); } } }
; #pragma unroll
;             for (int mm = 0; mm < RGB; ++mm) { const int q = rg * RGB + mm, ai = q >> 2, m = q & 3; float ssum = 0.f;
; #pragma unroll
;                 for (int bj = 0; bj < 2; ++bj) { const unsigned e = e0 + (unsigned)((ai * 128 + m * 16) * D + bj * 128);
;                     f32x4 r0, r1;
;                     if constexpr (INPLACE) { const u32x4 q4 = braw[mm][bj];
;                         r0 = (f32x4){__uint_as_float(q4[0] << 16), __uint_as_float(q4[0] & 0xffff0000u), __uint_as_float(q4[1] << 16), __uint_as_float(q4[1] & 0xffff0000u)};
;                         r1 = (f32x4){__uint_as_float(q4[2] << 16), __uint_as_float(q4[2] & 0xffff0000u), __uint_as_float(q4[3] << 16), __uint_as_float(q4[3] & 0xffff0000u)}; }
;                     else { r0 = bb[mm][bj][0]; r1 = bb[mm][bj][1]; }
;                     const f32x4 h0 = r0 + gv[bj][0] * (acc[ai][bj][m][0] + bv[bj][0]), h1 = r1 + gv[bj][1] * (acc[ai][bj][m][1] + bv[bj][1]);
;                     { u32x4 w; w.x = cvt_pk_bf16(h0[0], h0[1]); w.y = cvt_pk_bf16(h0[2], h0[3]); w.z = cvt_pk_bf16(h1[0], h1[1]); w.w = cvt_pk_bf16(h1[2], h1[3]); ST16(1, Hc + (size_t)(e * 2u), w); }
;                     if (FUSE) { ssum += ((h0[0] * h0[0] + h0[1] * h0[1]) + (h0[2] * h0[2] + h0[3] * h0[3])) + ((h1[0] * h1[0] + h1[1] * h1[1]) + (h1[2] * h1[2] + h1[3] * h1[3]));
;                         const f32x4 z0 = h0 * wv[bj][0], z1 = h1 * wv[bj][1];
;                         u32x4 w; w.x = cvt_pk_bf16(z0[0], z0[1]); w.y = cvt_pk_bf16(z0[2], z0[3]); w.z = cvt_pk_bf16(z1[0], z1[1]); w.w = cvt_pk_bf16(z1[2], z1[3]);
.LBB0_317:
	s_or_b64 exec, exec, s[38:39]
	v_add_u32_e32 v0, 0x20000, v231
	global_load_dwordx4 v[18:21], v0, s[16:17] nt
	global_load_dwordx4 v[166:169], v0, s[16:17] offset:16 nt
	v_add_u32_e32 v0, 0x20200, v231
	global_load_dwordx4 v[170:173], v0, s[16:17] nt
	global_load_dwordx4 v[196:199], v0, s[16:17] offset:16 nt
	v_add_u32_e32 v0, 0x30000, v231
	v_add_u32_e32 v4, 0x30200, v231
	global_load_dwordx4 v[8:11], v0, s[16:17] offset:16 nt
	global_load_dwordx4 v[12:15], v0, s[16:17] nt
	s_waitcnt lgkmcnt(0)
	global_load_dwordx4 v[0:3], v4, s[16:17] offset:16 nt
	s_nop 0
	global_load_dwordx4 v[4:7], v4, s[16:17] nt
	v_sub_u32_e32 v174, v232, v210
	v_add_u32_e32 v175, 0x10100, v210
	s_waitcnt vmcnt(7)
	v_pk_fma_f32 v[22:23], v[150:151], v[100:101], v[20:21]
	v_pk_fma_f32 v[150:151], v[152:153], v[98:99], v[18:19]
	s_waitcnt vmcnt(6)
	v_pk_fma_f32 v[152:153], v[154:155], v[102:103], v[168:169]
	v_pk_fma_f32 v[154:155], v[156:157], v[96:97], v[166:167]
	s_waitcnt vmcnt(5)
	v_pk_fma_f32 v[156:157], v[158:159], v[116:117], v[172:173]
	v_pk_fma_f32 v[158:159], v[160:161], v[114:115], v[170:171]
	s_waitcnt vmcnt(4)
	v_pk_fma_f32 v[160:161], v[162:163], v[118:119], v[198:199]
	v_pk_fma_f32 v[162:163], v[164:165], v[112:113], v[196:197]
	v_cvt_pk_bf16_f32 v18, v150, v151
	v_cvt_pk_bf16_f32 v19, v22, v23
	v_cvt_pk_bf16_f32 v20, v154, v155
	v_cvt_pk_bf16_f32 v21, v152, v153
	v_mul_f32_e32 v172, v151, v151
	v_mul_f32_e32 v173, v23, v23
	v_mul_f32_e32 v196, v155, v155
	v_mul_f32_e32 v197, v153, v153
	v_pk_mul_f32 v[164:165], v[74:75], v[22:23]
	v_pk_mul_f32 v[166:167], v[76:77], v[150:151]
	v_pk_mul_f32 v[168:169], v[78:79], v[152:153]
	v_pk_mul_f32 v[170:171], v[80:81], v[154:155]
	v_mul_f32_e32 v23, v159, v159
	v_mul_f32_e32 v151, v157, v157
	v_mul_f32_e32 v153, v163, v163
	v_mul_f32_e32 v155, v161, v161
	global_store_dwordx4 v174, v[18:21], s[26:27] nt
	v_fmac_f32_e32 v172, v150, v150
	v_fmac_f32_e32 v173, v22, v22
	v_fmac_f32_e32 v196, v154, v154
	v_fmac_f32_e32 v197, v152, v152
	v_cvt_pk_bf16_f32 v18, v166, v167
	v_fmac_f32_e32 v23, v158, v158
	v_fmac_f32_e32 v151, v156, v156
	v_fmac_f32_e32 v153, v162, v162
	v_fmac_f32_e32 v155, v160, v160
	v_cvt_pk_bf16_f32 v19, v164, v165
	v_cvt_pk_bf16_f32 v20, v170, v171
	v_cvt_pk_bf16_f32 v21, v168, v169
	v_add_f32_e32 v22, v172, v173
	v_add_f32_e32 v150, v196, v197
	global_store_dwordx4 v174, v[18:21], s[72:73]
	v_add_f32_e32 v23, v23, v151
	v_add_f32_e32 v151, v153, v155
	v_cvt_pk_bf16_f32 v18, v158, v159
	v_cvt_pk_bf16_f32 v19, v156, v157
	v_cvt_pk_bf16_f32 v20, v162, v163
	v_cvt_pk_bf16_f32 v21, v160, v161
	v_add_f32_e32 v22, v22, v150
	global_store_dwordx4 v175, v[18:21], s[26:27] nt
	v_pk_mul_f32 v[152:153], v[84:85], v[162:163]
	s_nop 0
	v_add_f32_e32 v18, v23, v151
	v_add_f32_e32 v21, v22, v18
	ds_bpermute_b32 v154, v16, v21
	v_pk_mul_f32 v[18:19], v[72:73], v[158:159]
	v_pk_mul_f32 v[22:23], v[90:91], v[156:157]
	v_cvt_pk_bf16_f32 v20, v18, v19
	v_pk_mul_f32 v[150:151], v[82:83], v[160:161]
	s_waitcnt lgkmcnt(0)
	v_add_f32_e32 v18, v21, v154
	ds_bpermute_b32 v19, v17, v18
	v_cvt_pk_bf16_f32 v21, v22, v23
	v_cvt_pk_bf16_f32 v22, v152, v153
	v_cvt_pk_bf16_f32 v23, v150, v151
	global_store_dwordx4 v175, v[20:23], s[72:73]
	s_and_saveexec_b64 s[38:39], s[0:1]
	s_cbranch_execz .LBB0_319
	v_or_b32_e32 v20, 32, v136
	v_mov_b32_e32 v21, v137
	v_lshl_add_u64 v[20:21], v[20:21], 2, s[24:25]
	s_waitcnt lgkmcnt(0)
	v_add_f32_e32 v18, v18, v19
	global_atomic_add_f32 v[20:21], v18, off

;     __device__ __forceinline__ void operator()(const f32x4 (&acc)[2][2][4][2], const Unit& u, int wr, int wc, int fr, int fq) const {
;     ...
;         for (int rg = 0; rg < 8 / RGB; ++rg) {
;             u32x4 braw[INPLACE ? RGB : 1][2]; f32x4 bb[INPLACE ? 1 : RGB][2][2];
; #pragma unroll
;             for (int mm = 0; mm < RGB; ++mm) { const int q = rg * RGB + mm, ai = q >> 2, m = q & 3;
; #pragma unroll
;                 for (int bj = 0; bj < 2; ++bj) { const unsigned e = e0 + (unsigned)((ai * 128 + m * 16) * D + bj * 128);
;                     if constexpr (INPLACE) braw[mm][bj] = *(const u32x4*)(Hc + (size_t)(e * 2u));
;                     else { bb[mm][bj][0] = *(const f32x4*)(bsc + (size_t)(e * 4u)); bb[mm][bj][1] = *(const f32x4*)(bsc + (size_t)(e * 4u + 16u)); } } }
; #pragma unroll
;             for (int mm = 0; mm < RGB; ++mm) { const int q = rg * RGB + mm, ai = q >> 2, m = q & 3; float ssum = 0.f;
; #pragma unroll
;                 for (int bj = 0; bj < 2; ++bj) { const unsigned e = e0 + (unsigned)((ai * 128 + m * 16) * D + bj * 128);
;                     f32x4 r0, r1;
;                     if constexpr (INPLACE) { const u32x4 q4 = braw[mm][bj];
;                         r0 = (f32x4){__uint_as_float(q4[0] << 16), __uint_as_float(q4[0] & 0xffff0000u), __uint_as_float(q4[1] << 16), __uint_as_float(q4[1] & 0xffff0000u)};
;                         r1 = (f32x4){__uint_as_float(q4[2] << 16), __uint_as_float(q4[2] & 0xffff0000u), __uint_as_float(q4[3] << 16), __uint_as_float(q4[3] & 0xffff0000u)}; }
;                     else { r0 = bb[mm][bj][0]; r1 = bb[mm][bj][1]; }
;                     const f32x4 h0 = r0 + gv[bj][0] * (acc[ai][bj][m][0] + bv[bj][0]), h1 = r1 + gv[bj][1] * (acc[ai][bj][m][1] + bv[bj][1]);
;                     { u32x4 w; w.x = cvt_pk_bf16(h0[0], h0[1]); w.y = cvt_pk_bf16(h0[2], h0[3]); w.z = cvt_pk_bf16(h1[0], h1[1]); w.w = cvt_pk_bf16(h1[2], h1[3]); ST16(1, Hc + (size_t)(e * 2u), w); }
;                     if (FUSE) { ssum += ((h0[0] * h0[0] + h0[1] * h0[1]) + (h0[2] * h0[2] + h0[3] * h0[3])) + ((h1[0] * h1[0] + h1[1] * h1[1]) + (h1[2] * h1[2] + h1[3] * h1[3]));
;                         const f32x4 z0 = h0 * wv[bj][0], z1 = h1 * wv[bj][1];
;                         u32x4 w; w.x = cvt_pk_bf16(z0[0], z0[1]); w.y = cvt_pk_bf16(z0[2], z0[3]); w.z = cvt_pk_bf16(z1[0], z1[1]); w.w = cvt_pk_bf16(z1[2], z1[3]);
.LBB0_321:
	s_or_b64 exec, exec, s[38:39]
	v_add_u32_e32 v0, 0x80000, v231
	global_load_dwordx4 v[18:21], v0, s[16:17] nt
	global_load_dwordx4 v[120:123], v0, s[16:17] offset:16 nt
	v_add_u32_e32 v0, 0x80200, v231
	global_load_dwordx4 v[124:127], v0, s[16:17] nt
	global_load_dwordx4 v[142:145], v0, s[16:17] offset:16 nt
	v_add_u32_e32 v0, 0x90000, v231
	v_add_u32_e32 v4, 0x90200, v231
	global_load_dwordx4 v[8:11], v0, s[16:17] offset:16 nt
	global_load_dwordx4 v[12:15], v0, s[16:17] nt
	s_waitcnt lgkmcnt(0)
	global_load_dwordx4 v[0:3], v4, s[16:17] offset:16 nt
	s_nop 0
	global_load_dwordx4 v[4:7], v4, s[16:17] nt
	v_add_u32_e32 v146, 0x40000, v210
	v_add_u32_e32 v147, 0x40100, v210
	s_waitcnt vmcnt(7)
	v_pk_fma_f32 v[22:23], v[86:87], v[100:101], v[20:21]
	v_pk_fma_f32 v[86:87], v[88:89], v[98:99], v[18:19]
	s_waitcnt vmcnt(6)
	v_pk_fma_f32 v[88:89], v[92:93], v[102:103], v[122:123]
	v_pk_fma_f32 v[92:93], v[94:95], v[96:97], v[120:121]
	s_waitcnt vmcnt(5)
	v_pk_fma_f32 v[94:95], v[104:105], v[116:117], v[126:127]
	v_pk_fma_f32 v[104:105], v[106:107], v[114:115], v[124:125]
	s_waitcnt vmcnt(4)
	v_pk_fma_f32 v[106:107], v[108:109], v[118:119], v[144:145]
	v_pk_fma_f32 v[108:109], v[110:111], v[112:113], v[142:143]
	v_cvt_pk_bf16_f32 v18, v86, v87
	v_cvt_pk_bf16_f32 v19, v22, v23
	v_cvt_pk_bf16_f32 v20, v92, v93
	v_cvt_pk_bf16_f32 v21, v88, v89
	v_mul_f32_e32 v126, v87, v87
	v_mul_f32_e32 v127, v23, v23
	v_mul_f32_e32 v142, v93, v93
	v_mul_f32_e32 v143, v89, v89
	v_pk_mul_f32 v[110:111], v[74:75], v[22:23]
	v_pk_mul_f32 v[120:121], v[76:77], v[86:87]
	v_pk_mul_f32 v[122:123], v[78:79], v[88:89]
	v_pk_mul_f32 v[124:125], v[80:81], v[92:93]
	v_mul_f32_e32 v23, v105, v105
	v_mul_f32_e32 v87, v95, v95
	v_mul_f32_e32 v89, v109, v109
	v_mul_f32_e32 v93, v107, v107
	global_store_dwordx4 v146, v[18:21], s[26:27] nt
	v_fmac_f32_e32 v126, v86, v86
	v_fmac_f32_e32 v127, v22, v22
	v_fmac_f32_e32 v142, v92, v92
	v_fmac_f32_e32 v143, v88, v88
	v_cvt_pk_bf16_f32 v18, v120, v121
	v_fmac_f32_e32 v23, v104, v104
	v_fmac_f32_e32 v87, v94, v94
	v_fmac_f32_e32 v89, v108, v108
	v_fmac_f32_e32 v93, v106, v106
	v_cvt_pk_bf16_f32 v19, v110, v111
	v_cvt_pk_bf16_f32 v20, v124, v125
	v_cvt_pk_bf16_f32 v21, v122, v123
	v_add_f32_e32 v22, v126, v127
	v_add_f32_e32 v86, v142, v143
	global_store_dwordx4 v146, v[18:21], s[72:73]
	v_add_f32_e32 v23, v23, v87
	v_add_f32_e32 v87, v89, v93
	v_cvt_pk_bf16_f32 v18, v104, v105
	v_cvt_pk_bf16_f32 v19, v94, v95
	v_cvt_pk_bf16_f32 v20, v108, v109
	v_cvt_pk_bf16_f32 v21, v106, v107
	v_add_f32_e32 v22, v22, v86
	global_store_dwordx4 v147, v[18:21], s[26:27] nt
	v_pk_mul_f32 v[88:89], v[84:85], v[108:109]
	s_nop 0
	v_add_f32_e32 v18, v23, v87
	v_add_f32_e32 v21, v22, v18
	ds_bpermute_b32 v92, v16, v21
	v_pk_mul_f32 v[18:19], v[72:73], v[104:105]
	v_pk_mul_f32 v[22:23], v[90:91], v[94:95]
	v_cvt_pk_bf16_f32 v20, v18, v19
	v_pk_mul_f32 v[86:87], v[82:83], v[106:107]
	s_waitcnt lgkmcnt(0)
	v_add_f32_e32 v18, v21, v92
	ds_bpermute_b32 v19, v17, v18
	v_cvt_pk_bf16_f32 v21, v22, v23
	v_cvt_pk_bf16_f32 v22, v88, v89
	v_cvt_pk_bf16_f32 v23, v86, v87
	global_store_dwordx4 v147, v[20:23], s[72:73]
	s_and_saveexec_b64 s[38:39], s[0:1]
	s_cbranch_execz .LBB0_323
	v_add_u32_e32 v20, 0x80, v136
	v_mov_b32_e32 v21, v137
	v_lshl_add_u64 v[20:21], v[20:21], 2, s[24:25]
	s_waitcnt lgkmcnt(0)
	v_add_f32_e32 v18, v18, v19
	global_atomic_add_f32 v[20:21], v18, off

;     __device__ __forceinline__ void operator()(const f32x4 (&acc)[2][2][4][2], const Unit& u, int wr, int wc, int fr, int fq) const {
;     ...
;         for (int rg = 0; rg < 8 / RGB; ++rg) {
;             u32x4 braw[INPLACE ? RGB : 1][2]; f32x4 bb[INPLACE ? 1 : RGB][2][2];
; #pragma unroll
;             for (int mm = 0; mm < RGB; ++mm) { const int q = rg * RGB + mm, ai = q >> 2, m = q & 3;
; #pragma unroll
;                 for (int bj = 0; bj < 2; ++bj) { const unsigned e = e0 + (unsigned)((ai * 128 + m * 16) * D + bj * 128);
;                     if constexpr (INPLACE) braw[mm][bj] = *(const u32x4*)(Hc + (size_t)(e * 2u));
;                     else { bb[mm][bj][0] = *(const f32x4*)(bsc + (size_t)(e * 4u)); bb[mm][bj][1] = *(const f32x4*)(bsc + (size_t)(e * 4u + 16u)); } } }
; #pragma unroll
;             for (int mm = 0; mm < RGB; ++mm) { const int q = rg * RGB + mm, ai = q >> 2, m = q & 3; float ssum = 0.f;
; #pragma unroll
;                 for (int bj = 0; bj < 2; ++bj) { const unsigned e = e0 + (unsigned)((ai * 128 + m * 16) * D + bj * 128);
;                     f32x4 r0, r1;
;                     if constexpr (INPLACE) { const u32x4 q4 = braw[mm][bj];
;                         r0 = (f32x4){__uint_as_float(q4[0] << 16), __uint_as_float(q4[0] & 0xffff0000u), __uint_as_float(q4[1] << 16), __uint_as_float(q4[1] & 0xffff0000u)};
;                         r1 = (f32x4){__uint_as_float(q4[2] << 16), __uint_as_float(q4[2] & 0xffff0000u), __uint_as_float(q4[3] << 16), __uint_as_float(q4[3] & 0xffff0000u)}; }
;                     else { r0 = bb[mm][bj][0]; r1 = bb[mm][bj][1]; }
;                     const f32x4 h0 = r0 + gv[bj][0] * (acc[ai][bj][m][0] + bv[bj][0]), h1 = r1 + gv[bj][1] * (acc[ai][bj][m][1] + bv[bj][1]);
;                     { u32x4 w; w.x = cvt_pk_bf16(h0[0], h0[1]); w.y = cvt_pk_bf16(h0[2], h0[3]); w.z = cvt_pk_bf16(h1[0], h1[1]); w.w = cvt_pk_bf16(h1[2], h1[3]); ST16(1, Hc + (size_t)(e * 2u), w); }
;                     if (FUSE) { ssum += ((h0[0] * h0[0] + h0[1] * h0[1]) + (h0[2] * h0[2] + h0[3] * h0[3])) + ((h1[0] * h1[0] + h1[1] * h1[1]) + (h1[2] * h1[2] + h1[3] * h1[3]));
;                         const f32x4 z0 = h0 * wv[bj][0], z1 = h1 * wv[bj][1];
;                         u32x4 w; w.x = cvt_pk_bf16(z0[0], z0[1]); w.y = cvt_pk_bf16(z0[2], z0[3]); w.z = cvt_pk_bf16(z1[0], z1[1]); w.w = cvt_pk_bf16(z1[2], z1[3]);
.LBB0_325:
	s_or_b64 exec, exec, s[38:39]
	v_add_u32_e32 v0, 0xa0000, v231
	global_load_dwordx4 v[18:21], v0, s[16:17] nt
	global_load_dwordx4 v[56:59], v0, s[16:17] offset:16 nt
	v_add_u32_e32 v0, 0xa0200, v231
	global_load_dwordx4 v[60:63], v0, s[16:17] nt
	global_load_dwordx4 v[64:67], v0, s[16:17] offset:16 nt
	v_add_u32_e32 v0, 0xb0000, v231
	v_add_u32_e32 v4, 0xb0200, v231
	global_load_dwordx4 v[8:11], v0, s[16:17] offset:16 nt
	global_load_dwordx4 v[12:15], v0, s[16:17] nt
	s_waitcnt lgkmcnt(0)
	global_load_dwordx4 v[0:3], v4, s[16:17] offset:16 nt
	s_nop 0
	global_load_dwordx4 v[4:7], v4, s[16:17] nt
	v_add_u32_e32 v68, 0x50000, v210
	v_add_u32_e32 v69, 0x50100, v210
	s_waitcnt vmcnt(7)
	v_pk_fma_f32 v[22:23], v[42:43], v[100:101], v[20:21]
	v_pk_fma_f32 v[40:41], v[40:41], v[98:99], v[18:19]
	s_waitcnt vmcnt(6)
	v_pk_fma_f32 v[42:43], v[44:45], v[102:103], v[58:59]
	v_pk_fma_f32 v[44:45], v[46:47], v[96:97], v[56:57]
	s_waitcnt vmcnt(5)
	v_pk_fma_f32 v[46:47], v[48:49], v[116:117], v[62:63]
	v_pk_fma_f32 v[48:49], v[50:51], v[114:115], v[60:61]
	s_waitcnt vmcnt(4)
	v_pk_fma_f32 v[50:51], v[52:53], v[118:119], v[66:67]
	v_pk_fma_f32 v[52:53], v[54:55], v[112:113], v[64:65]
	v_cvt_pk_bf16_f32 v18, v40, v41
	v_cvt_pk_bf16_f32 v19, v22, v23
	v_cvt_pk_bf16_f32 v20, v44, v45
	v_cvt_pk_bf16_f32 v21, v42, v43
	v_mul_f32_e32 v62, v41, v41
	v_mul_f32_e32 v63, v23, v23
	v_mul_f32_e32 v64, v45, v45
	v_mul_f32_e32 v65, v43, v43
	v_pk_mul_f32 v[54:55], v[74:75], v[22:23]
	v_pk_mul_f32 v[56:57], v[76:77], v[40:41]
	v_pk_mul_f32 v[58:59], v[78:79], v[42:43]
	v_pk_mul_f32 v[60:61], v[80:81], v[44:45]
	v_mul_f32_e32 v23, v49, v49
	v_mul_f32_e32 v41, v47, v47
	v_mul_f32_e32 v43, v53, v53
	v_mul_f32_e32 v45, v51, v51
	global_store_dwordx4 v68, v[18:21], s[26:27] nt
	v_fmac_f32_e32 v62, v40, v40
	v_fmac_f32_e32 v63, v22, v22
	v_fmac_f32_e32 v64, v44, v44
	v_fmac_f32_e32 v65, v42, v42
	v_cvt_pk_bf16_f32 v18, v56, v57
	v_fmac_f32_e32 v23, v48, v48
	v_fmac_f32_e32 v41, v46, v46
	v_fmac_f32_e32 v43, v52, v52
	v_fmac_f32_e32 v45, v50, v50
	v_cvt_pk_bf16_f32 v19, v54, v55
	v_cvt_pk_bf16_f32 v20, v60, v61
	v_cvt_pk_bf16_f32 v21, v58, v59
	v_add_f32_e32 v22, v62, v63
	v_add_f32_e32 v40, v64, v65
	global_store_dwordx4 v68, v[18:21], s[72:73]
	v_add_f32_e32 v23, v23, v41
	v_add_f32_e32 v41, v43, v45
	v_cvt_pk_bf16_f32 v18, v48, v49
	v_cvt_pk_bf16_f32 v19, v46, v47
	v_cvt_pk_bf16_f32 v20, v52, v53
	v_cvt_pk_bf16_f32 v21, v50, v51
	v_add_f32_e32 v22, v22, v40
	global_store_dwordx4 v69, v[18:21], s[26:27] nt
	v_pk_mul_f32 v[42:43], v[84:85], v[52:53]
	s_nop 0
	v_add_f32_e32 v18, v23, v41
	v_add_f32_e32 v21, v22, v18
	ds_bpermute_b32 v44, v16, v21
	v_pk_mul_f32 v[18:19], v[72:73], v[48:49]
	v_pk_mul_f32 v[22:23], v[90:91], v[46:47]
	v_cvt_pk_bf16_f32 v20, v18, v19
	v_pk_mul_f32 v[40:41], v[82:83], v[50:51]
	s_waitcnt lgkmcnt(0)
	v_add_f32_e32 v18, v21, v44
	ds_bpermute_b32 v19, v17, v18
	v_cvt_pk_bf16_f32 v21, v22, v23
	v_cvt_pk_bf16_f32 v22, v42, v43
	v_cvt_pk_bf16_f32 v23, v40, v41
	global_store_dwordx4 v69, v[20:23], s[72:73]
	s_and_saveexec_b64 s[38:39], s[0:1]
	s_cbranch_execz .LBB0_327
	v_add_u32_e32 v20, 0xa0, v136
	v_mov_b32_e32 v21, v137
	v_lshl_add_u64 v[20:21], v[20:21], 2, s[24:25]
	s_waitcnt lgkmcnt(0)
	v_add_f32_e32 v18, v18, v19
	global_atomic_add_f32 v[20:21], v18, off
